# P5: next unit's ln_g/ln_b loads issued in the epilogue tail (accumulators dead) with a counted vmcnt(4) after the 4th store, so the loop top no longer waits for L2 latency and store acks
# baseline (speedup 1.0000x reference)
; __device__ __forceinline__ bf16x8 tobf8(f32x8 x) { u32x4 w = {cvtpk(x[0], x[1]), cvtpk(x[2], x[3]), cvtpk(x[4], x[5]), cvtpk(x[6], x[7])}; return *reinterpret_cast<bf16x8*>(&w); }
; __device__ __forceinline__ void spatial_phase(const Params& p, char* lds) {
;     ...
;         if (g != g_loaded) { g_loaded = g;
; #pragma unroll
;             for (int st_ = 0; st_ < 2; ++st_)
; #pragma unroll
;                 for (int ks = 0; ks < 4; ++ks) { const int s0 = 64 * st_ + 16 * ks + 8 * hi; const float* wp = p.w_sp + ((size_t)g * CCH + t) * CCH + s0;
;                     const f32x4 a = *(const f32x4*)wp, c = *(const f32x4*)(wp + 4); f32x8 y;
; #pragma unroll
;                     for (int i = 0; i < 4; ++i) { y[i] = (s0 + i <= t) ? a[i] : 0.f; y[4 + i] = (s0 + 4 + i <= t) ? c[i] : 0.f; }
;                     pa[st_][ks] = tobf8(y); }
.LBB0_1200:
	s_and_b32 s42, s79, 15
	s_cmp_eq_u32 s42, s33
	s_cbranch_scc1 .LBB0_1202
	s_waitcnt vmcnt(0)
	s_mov_b32 s101, 0
	v_lshl_or_b32 v0, s42, 16, v209
	v_mov_b32_e32 v1, v96
	v_lshl_add_u64 v[0:1], v[224:225], 0, v[0:1]
	global_load_dwordx4 v[24:27], v[0:1], off
	global_load_dwordx4 v[28:31], v[0:1], off offset:16
	global_load_dwordx4 v[32:35], v[0:1], off offset:64
	global_load_dwordx4 v[36:39], v[0:1], off offset:80
	global_load_dwordx4 v[40:43], v[0:1], off offset:128
	global_load_dwordx4 v[44:47], v[0:1], off offset:144
	global_load_dwordx4 v[48:51], v[0:1], off offset:192
	global_load_dwordx4 v[52:55], v[0:1], off offset:208
	global_load_dwordx4 v[56:59], v[0:1], off offset:256
	global_load_dwordx4 v[60:63], v[0:1], off offset:272
	global_load_dwordx4 v[100:103], v[0:1], off offset:320
	global_load_dwordx4 v[104:107], v[0:1], off offset:336
	global_load_dwordx4 v[108:111], v[0:1], off offset:384
	global_load_dwordx4 v[112:115], v[0:1], off offset:400
	global_load_dwordx4 v[116:119], v[0:1], off offset:448
	global_load_dwordx4 v[120:123], v[0:1], off offset:464
	s_waitcnt vmcnt(0)
	v_readlane_b32 s38, v253, 16
	v_readlane_b32 s39, v253, 17
	v_readlane_b32 s52, v253, 0
	v_readlane_b32 s53, v253, 1
	s_mov_b32 s33, s42
	v_readlane_b32 s54, v253, 2
	v_readlane_b32 s55, v253, 3
	v_readlane_b32 s56, v253, 4
	v_readlane_b32 s57, v253, 5
	v_readlane_b32 s58, v253, 6
	v_readlane_b32 s59, v253, 7
	v_mov_b32_e32 v2, v24
	v_mov_b32_e32 v3, v25
	v_mov_b32_e32 v4, v26
	v_mov_b32_e32 v5, v27
	v_cndmask_b32_e64 v2, v2, 0, s[38:39]
	v_readlane_b32 s38, v253, 53
	v_readlane_b32 s39, v253, 54
	v_mov_b32_e32 v6, v28
	v_mov_b32_e32 v7, v29
	v_mov_b32_e32 v8, v30
	v_mov_b32_e32 v9, v31
	s_nop 0
	v_cndmask_b32_e64 v6, v6, 0, s[38:39]
	v_readlane_b32 s38, v253, 57
	v_readlane_b32 s39, v253, 58
	s_nop 1
	v_cndmask_b32_e64 v3, 0, v3, s[38:39]
	v_readlane_b32 s38, v253, 59
	v_readlane_b32 s39, v253, 60
	v_cvt_pk_bf16_f32 v132, v2, v3
	s_nop 1
	v_cndmask_b32_e64 v7, v7, 0, s[38:39]
	v_readlane_b32 s38, v253, 61
	v_readlane_b32 s39, v253, 62
	s_nop 1
	v_cndmask_b32_e64 v4, v4, 0, s[38:39]
	v_readlane_b32 s38, v253, 63
	v_readlane_b32 s39, v254, 0
	s_nop 1
	v_cndmask_b32_e64 v8, v8, 0, s[38:39]
	v_readlane_b32 s38, v254, 1
	v_readlane_b32 s39, v254, 2
	s_nop 1
	v_cndmask_b32_e64 v5, v5, 0, s[38:39]
	v_readlane_b32 s38, v254, 3
	v_readlane_b32 s39, v254, 4
	v_cvt_pk_bf16_f32 v133, v4, v5
	v_cvt_pk_bf16_f32 v134, v6, v7
	s_nop 1
	v_cndmask_b32_e64 v9, v9, 0, s[38:39]
	v_cvt_pk_bf16_f32 v135, v8, v9
	v_readlane_b32 s38, v254, 5
	v_readlane_b32 s39, v254, 6
	v_mov_b32_e32 v2, v32
	v_mov_b32_e32 v3, v33
	v_mov_b32_e32 v4, v34
	v_mov_b32_e32 v5, v35
	s_nop 0
	v_cndmask_b32_e64 v2, v2, 0, s[38:39]
	v_readlane_b32 s38, v253, 55
	v_readlane_b32 s39, v253, 56
	v_mov_b32_e32 v6, v36
	v_mov_b32_e32 v7, v37
	v_mov_b32_e32 v8, v38
	v_mov_b32_e32 v9, v39
	s_nop 0
	v_cndmask_b32_e64 v6, v6, 0, s[38:39]
	v_readlane_b32 s38, v254, 7
	v_readlane_b32 s39, v254, 8
	s_nop 1
	v_cndmask_b32_e64 v3, v3, 0, s[38:39]
	v_readlane_b32 s38, v254, 9
	v_readlane_b32 s39, v254, 10
	v_cvt_pk_bf16_f32 v136, v2, v3
	s_nop 1
	v_cndmask_b32_e64 v7, v7, 0, s[38:39]
	v_readlane_b32 s38, v254, 11
	v_readlane_b32 s39, v254, 12
	s_nop 1
	v_cndmask_b32_e64 v4, v4, 0, s[38:39]
	v_readlane_b32 s38, v254, 13
	v_readlane_b32 s39, v254, 14
	s_nop 1
	v_cndmask_b32_e64 v8, v8, 0, s[38:39]
	v_readlane_b32 s38, v254, 15
	v_readlane_b32 s39, v254, 16
	s_nop 1
	v_cndmask_b32_e64 v5, v5, 0, s[38:39]
	v_readlane_b32 s38, v253, 49
	v_readlane_b32 s39, v253, 50
	v_cvt_pk_bf16_f32 v137, v4, v5
	v_cvt_pk_bf16_f32 v138, v6, v7
	s_nop 1
	v_cndmask_b32_e64 v9, v9, 0, s[38:39]
	v_cvt_pk_bf16_f32 v139, v8, v9
	v_readlane_b32 s38, v254, 17
	v_readlane_b32 s39, v254, 18
	v_mov_b32_e32 v2, v40
	v_mov_b32_e32 v3, v41
	v_mov_b32_e32 v4, v42
	v_mov_b32_e32 v5, v43
	s_nop 0
	v_cndmask_b32_e64 v2, v2, 0, s[38:39]
	v_readlane_b32 s38, v253, 51
	v_readlane_b32 s39, v253, 52
	v_mov_b32_e32 v6, v44
	v_mov_b32_e32 v7, v45
	v_mov_b32_e32 v8, v46
	v_mov_b32_e32 v9, v47
	s_nop 0
	v_cndmask_b32_e64 v6, v6, 0, s[38:39]
	v_readlane_b32 s38, v254, 19
	v_readlane_b32 s39, v254, 20
	s_nop 1
	v_cndmask_b32_e64 v3, v3, 0, s[38:39]
	v_readlane_b32 s38, v254, 21
	v_readlane_b32 s39, v254, 22
	v_cvt_pk_bf16_f32 v140, v2, v3
	s_nop 1
	v_cndmask_b32_e64 v7, v7, 0, s[38:39]
	v_readlane_b32 s38, v254, 23
	v_readlane_b32 s39, v254, 24
	s_nop 1
	v_cndmask_b32_e64 v4, v4, 0, s[38:39]
	v_readlane_b32 s38, v254, 25
	v_readlane_b32 s39, v254, 26
	s_nop 1
	v_cndmask_b32_e64 v8, v8, 0, s[38:39]
	v_readlane_b32 s38, v254, 27
	v_readlane_b32 s39, v254, 28
	s_nop 1
	v_cndmask_b32_e64 v5, v5, 0, s[38:39]
	v_readlane_b32 s38, v254, 29
	v_readlane_b32 s39, v254, 30
	v_cvt_pk_bf16_f32 v141, v4, v5
	v_cvt_pk_bf16_f32 v142, v6, v7
	s_nop 1
	v_cndmask_b32_e64 v9, v9, 0, s[38:39]
	v_cvt_pk_bf16_f32 v143, v8, v9
	v_readlane_b32 s38, v254, 31
	v_readlane_b32 s39, v254, 32
	v_mov_b32_e32 v2, v48
	v_mov_b32_e32 v3, v49
	v_mov_b32_e32 v4, v50
	v_mov_b32_e32 v5, v51
	s_nop 0
	v_cndmask_b32_e64 v2, v2, 0, s[38:39]
	v_readlane_b32 s38, v254, 33
; __device__ __forceinline__ int crow(int r, int hi) { return (r & 3) + 8 * (r >> 2) + 4 * hi; }
; __device__ __forceinline__ bf16x8 tobf8(f32x8 x) { u32x4 w = {cvtpk(x[0], x[1]), cvtpk(x[2], x[3]), cvtpk(x[4], x[5]), cvtpk(x[6], x[7])}; return *reinterpret_cast<bf16x8*>(&w); }
; __device__ __forceinline__ void spatial_phase(const Params& p, char* lds) {
;     ...
;                 for (int ks = 0; ks < 4; ++ks) { const int s0 = 64 * st_ + 16 * ks + 8 * hi; const float* wp = p.w_sp + ((size_t)g * CCH + t) * CCH + s0;
;                     const f32x4 a = *(const f32x4*)wp, c = *(const f32x4*)(wp + 4); f32x8 y;
; #pragma unroll
;                     for (int i = 0; i < 4; ++i) { y[i] = (s0 + i <= t) ? a[i] : 0.f; y[4 + i] = (s0 + 4 + i <= t) ? c[i] : 0.f; }
;                     pa[st_][ks] = tobf8(y); }
; #pragma unroll
;             for (int r = 0; r < 16; ++r) bsp_[r] = p.b_sp[g * CCH + 32 * tb + crow(r, hi)]; }
;     ...
;                     const f32x4 g0 = *(const f32x4*)(p.ln_g + g * GD + cc), g1 = *(const f32x4*)(p.ln_g + g * GD + cc + 4), b0 = *(const f32x4*)(p.ln_b + g * GD + cc), b1 = *(const f32x4*)(p.ln_b + g * GD + cc + 4);
	v_readlane_b32 s39, v254, 34
	v_mov_b32_e32 v6, v52
	v_mov_b32_e32 v7, v53
	v_mov_b32_e32 v8, v54
	v_mov_b32_e32 v9, v55
	s_nop 0
	v_cndmask_b32_e64 v6, v6, 0, s[38:39]
	v_readlane_b32 s38, v254, 35
	v_readlane_b32 s39, v254, 36
	s_nop 1
	v_cndmask_b32_e64 v3, v3, 0, s[38:39]
	v_readlane_b32 s38, v254, 37
	v_readlane_b32 s39, v254, 38
	v_cvt_pk_bf16_f32 v144, v2, v3
	s_nop 1
	v_cndmask_b32_e64 v7, v7, 0, s[38:39]
	v_readlane_b32 s38, v254, 39
	v_readlane_b32 s39, v254, 40
	s_nop 1
	v_cndmask_b32_e64 v4, v4, 0, s[38:39]
	v_readlane_b32 s38, v254, 41
	v_readlane_b32 s39, v254, 42
	s_nop 1
	v_cndmask_b32_e64 v8, v8, 0, s[38:39]
	v_readlane_b32 s38, v254, 43
	v_readlane_b32 s39, v254, 44
	s_nop 1
	v_cndmask_b32_e64 v5, v5, 0, s[38:39]
	v_readlane_b32 s38, v254, 45
	v_readlane_b32 s39, v254, 46
	v_cvt_pk_bf16_f32 v145, v4, v5
	v_cvt_pk_bf16_f32 v146, v6, v7
	s_nop 1
	v_cndmask_b32_e64 v9, v9, 0, s[38:39]
	v_cvt_pk_bf16_f32 v147, v8, v9
	v_readlane_b32 s38, v254, 47
	v_readlane_b32 s39, v254, 48
	v_mov_b32_e32 v2, v56
	v_mov_b32_e32 v3, v57
	v_mov_b32_e32 v4, v58
	v_mov_b32_e32 v5, v59
	s_nop 0
	v_cndmask_b32_e64 v2, v2, 0, s[38:39]
	v_readlane_b32 s38, v254, 49
	v_readlane_b32 s39, v254, 50
	v_mov_b32_e32 v6, v60
	v_mov_b32_e32 v7, v61
	v_mov_b32_e32 v8, v62
	v_mov_b32_e32 v9, v63
	s_nop 0
	v_cndmask_b32_e64 v6, v6, 0, s[38:39]
	v_readlane_b32 s38, v254, 51
	v_readlane_b32 s39, v254, 52
	s_nop 1
	v_cndmask_b32_e64 v3, v3, 0, s[38:39]
	v_readlane_b32 s38, v254, 53
	v_readlane_b32 s39, v254, 54
	v_cvt_pk_bf16_f32 v148, v2, v3
	s_nop 1
	v_cndmask_b32_e64 v7, v7, 0, s[38:39]
	v_readlane_b32 s38, v254, 55
	v_readlane_b32 s39, v254, 56
	s_nop 1
	v_cndmask_b32_e64 v4, v4, 0, s[38:39]
	v_readlane_b32 s38, v254, 57
	v_readlane_b32 s39, v254, 58
	s_nop 1
	v_cndmask_b32_e64 v8, v8, 0, s[38:39]
	v_readlane_b32 s38, v254, 59
	v_readlane_b32 s39, v254, 60
	s_nop 1
	v_cndmask_b32_e64 v5, v5, 0, s[38:39]
	v_readlane_b32 s38, v254, 61
	v_readlane_b32 s39, v254, 62
	v_cvt_pk_bf16_f32 v149, v4, v5
	v_cvt_pk_bf16_f32 v150, v6, v7
	s_nop 1
	v_cndmask_b32_e64 v9, v9, 0, s[38:39]
	v_cvt_pk_bf16_f32 v151, v8, v9
	v_readlane_b32 s38, v254, 63
	v_readlane_b32 s39, v255, 0
	v_mov_b32_e32 v2, v100
	v_mov_b32_e32 v3, v101
	v_mov_b32_e32 v4, v102
	v_mov_b32_e32 v5, v103
	v_cndmask_b32_e64 v4, v4, 0, s[84:85]
	v_cndmask_b32_e64 v2, v2, 0, s[38:39]
	v_readlane_b32 s38, v255, 1
	v_readlane_b32 s39, v255, 2
	v_mov_b32_e32 v6, v104
	v_mov_b32_e32 v7, v105
	v_mov_b32_e32 v8, v106
	v_mov_b32_e32 v9, v107
	v_cndmask_b32_e64 v7, v7, 0, s[50:51]
	v_cndmask_b32_e64 v8, v8, 0, s[88:89]
	v_cndmask_b32_e64 v6, v6, 0, s[38:39]
	v_readlane_b32 s38, v255, 3
	v_readlane_b32 s39, v255, 4
	v_cndmask_b32_e64 v5, v5, 0, s[96:97]
	v_cndmask_b32_e64 v9, v9, 0, s[0:1]
	v_cndmask_b32_e64 v3, v3, 0, s[38:39]
	v_cvt_pk_bf16_f32 v152, v2, v3
	v_cvt_pk_bf16_f32 v153, v4, v5
	v_cvt_pk_bf16_f32 v154, v6, v7
	v_cvt_pk_bf16_f32 v155, v8, v9
	v_mov_b32_e32 v2, v108
	v_mov_b32_e32 v3, v109
	v_mov_b32_e32 v4, v110
	v_mov_b32_e32 v5, v111
	v_cndmask_b32_e64 v2, v2, 0, s[2:3]
	v_mov_b32_e32 v6, v112
	v_mov_b32_e32 v7, v113
	v_mov_b32_e32 v8, v114
	v_mov_b32_e32 v9, v115
	v_cndmask_b32_e64 v6, v6, 0, s[4:5]
	v_cndmask_b32_e64 v3, v3, 0, s[6:7]
	v_cndmask_b32_e64 v7, v7, 0, s[8:9]
	v_cndmask_b32_e64 v4, v4, 0, s[10:11]
	v_cndmask_b32_e64 v8, v8, 0, s[12:13]
	v_cndmask_b32_e64 v5, v5, 0, s[14:15]
	v_cndmask_b32_e64 v9, v9, 0, s[16:17]
	v_cvt_pk_bf16_f32 v156, v2, v3
	v_cvt_pk_bf16_f32 v157, v4, v5
	v_cvt_pk_bf16_f32 v158, v6, v7
	v_cvt_pk_bf16_f32 v159, v8, v9
	v_lshl_or_b32 v0, s42, 9, v211
	v_mov_b32_e32 v2, v116
	v_mov_b32_e32 v3, v117
	v_mov_b32_e32 v4, v118
	v_mov_b32_e32 v5, v119
	v_cndmask_b32_e64 v1, v2, 0, s[18:19]
	v_mov_b32_e32 v6, v120
	v_mov_b32_e32 v7, v121
	v_mov_b32_e32 v8, v122
	v_mov_b32_e32 v9, v123
	v_cndmask_b32_e64 v2, v6, 0, s[20:21]
	v_cndmask_b32_e64 v3, v3, 0, s[22:23]
	v_cndmask_b32_e64 v6, v7, 0, s[24:25]
	v_cndmask_b32_e64 v4, v4, 0, s[26:27]
	v_cndmask_b32_e64 v7, v8, 0, s[28:29]
	v_cndmask_b32_e64 v5, v5, 0, s[30:31]
	v_cndmask_b32_e64 v8, v9, 0, s[34:35]
	v_cvt_pk_bf16_f32 v160, v1, v3
	v_cvt_pk_bf16_f32 v161, v4, v5
	v_cvt_pk_bf16_f32 v162, v2, v6
	v_cvt_pk_bf16_f32 v163, v7, v8
	global_load_dwordx4 v[164:167], v0, s[52:53]
	global_load_dwordx4 v[168:171], v0, s[52:53] offset:32
	global_load_dwordx4 v[172:175], v0, s[52:53] offset:64
	global_load_dwordx4 v[176:179], v0, s[52:53] offset:96
.LBB0_1202:
	s_cmp_eq_u32 s101, 1
	s_mov_b32 s101, 0
	s_cbranch_scc1 .Lp5ln_have
	s_lshl_b32 s74, s42, 10
	v_lshl_add_u64 v[22:23], v[220:221], 0, s[74:75]
	v_lshl_add_u64 v[24:25], v[222:223], 0, s[74:75]
	global_load_dwordx4 v[32:35], v[22:23], off
	global_load_dwordx4 v[36:39], v[22:23], off offset:16
	global_load_dwordx4 v[48:51], v[22:23], off offset:512
	global_load_dwordx4 v[52:55], v[22:23], off offset:528
	global_load_dwordx4 v[40:43], v[24:25], off
	global_load_dwordx4 v[44:47], v[24:25], off offset:16
	global_load_dwordx4 v[56:59], v[24:25], off offset:512
	global_load_dwordx4 v[60:63], v[24:25], off offset:528
	s_waitcnt vmcnt(0)

; __device__ __forceinline__ unsigned cvtpk(float lo, float hi) { unsigned r; asm volatile("v_cvt_pk_bf16_f32 %0, %1, %2" : "=v"(r) : "v"(lo), "v"(hi)); return r; }
; __device__ __forceinline__ int crow(int r, int hi) { return (r & 3) + 8 * (r >> 2) + 4 * hi; }
; __device__ __forceinline__ void spatial_phase(const Params& p, char* lds) {
;     ...
;             for (int r = 0; r < 16; ++r) { const int tl = crow(r, hi); const float bsp = bsp_[r];
; #pragma unroll
;                 for (int d0 = 0; d0 < 4; ++d0) { const unsigned pk = cvtpk(o[d0][r] + bsp, 0.f); *(bf16_t*)(stg + tl * 256 + (d0 * 32 + r32) * 2) = (bf16_t)(pk & 0xffffu); } }
.LBB0_1266:
	v_add_f32_e32 v0, v164, v0
	v_cvt_pk_bf16_f32 v0, v0, v96
	ds_write_b16 v189, v0
	s_nop 0
	v_add_f32_e32 v0, v164, v16
	v_cvt_pk_bf16_f32 v0, v0, v96
	ds_write_b16 v189, v0 offset:64
	s_nop 1
	v_add_f32_e32 v0, v164, v32
	v_cvt_pk_bf16_f32 v0, v0, v96
	ds_write_b16 v189, v0 offset:128
	s_nop 1
	v_add_f32_e32 v0, v164, v48
	v_cvt_pk_bf16_f32 v0, v0, v96
	ds_write_b16 v189, v0 offset:192
	v_add_f32_e32 v0, v165, v1
	v_cvt_pk_bf16_f32 v0, v0, v96
	ds_write_b16 v189, v0 offset:256
	v_add_f32_e32 v0, v165, v17
	v_cvt_pk_bf16_f32 v0, v0, v96
	ds_write_b16 v189, v0 offset:320
	v_add_f32_e32 v0, v165, v33
	v_cvt_pk_bf16_f32 v0, v0, v96
	ds_write_b16 v189, v0 offset:384
	v_add_f32_e32 v0, v165, v49
	v_cvt_pk_bf16_f32 v0, v0, v96
	ds_write_b16 v189, v0 offset:448
	v_add_f32_e32 v0, v166, v2
	v_cvt_pk_bf16_f32 v0, v0, v96
	ds_write_b16 v189, v0 offset:512
	v_add_f32_e32 v0, v166, v18
	v_cvt_pk_bf16_f32 v0, v0, v96
	ds_write_b16 v189, v0 offset:576
	v_add_f32_e32 v0, v166, v34
	v_cvt_pk_bf16_f32 v0, v0, v96
	ds_write_b16 v189, v0 offset:640
	v_add_f32_e32 v0, v166, v50
	v_cvt_pk_bf16_f32 v0, v0, v96
	ds_write_b16 v189, v0 offset:704
	v_add_f32_e32 v0, v167, v3
	v_cvt_pk_bf16_f32 v0, v0, v96
	ds_write_b16 v189, v0 offset:768
	v_add_f32_e32 v0, v167, v19
	v_cvt_pk_bf16_f32 v0, v0, v96
	ds_write_b16 v189, v0 offset:832
	v_add_f32_e32 v0, v167, v35
	v_cvt_pk_bf16_f32 v0, v0, v96
	ds_write_b16 v189, v0 offset:896
	v_add_f32_e32 v0, v167, v51
	v_cvt_pk_bf16_f32 v0, v0, v96
	ds_write_b16 v189, v0 offset:960
	v_add_f32_e32 v0, v168, v4
	v_cvt_pk_bf16_f32 v0, v0, v96
	ds_write_b16 v189, v0 offset:2048
	v_add_f32_e32 v0, v168, v20
	v_cvt_pk_bf16_f32 v0, v0, v96
	ds_write_b16 v189, v0 offset:2112
	v_add_f32_e32 v0, v168, v36
	v_cvt_pk_bf16_f32 v0, v0, v96
	ds_write_b16 v189, v0 offset:2176
	v_add_f32_e32 v0, v168, v52
	v_cvt_pk_bf16_f32 v0, v0, v96
	ds_write_b16 v189, v0 offset:2240
	v_add_f32_e32 v0, v169, v5
	v_cvt_pk_bf16_f32 v0, v0, v96
	ds_write_b16 v189, v0 offset:2304
	v_add_f32_e32 v0, v169, v21
	v_cvt_pk_bf16_f32 v0, v0, v96
	ds_write_b16 v189, v0 offset:2368
	v_add_f32_e32 v0, v169, v37
	v_cvt_pk_bf16_f32 v0, v0, v96
	ds_write_b16 v189, v0 offset:2432
	v_add_f32_e32 v0, v169, v53
	v_cvt_pk_bf16_f32 v0, v0, v96
	ds_write_b16 v189, v0 offset:2496
	v_add_f32_e32 v0, v170, v6
	v_cvt_pk_bf16_f32 v0, v0, v96
	ds_write_b16 v189, v0 offset:2560
	v_add_f32_e32 v0, v170, v22
	v_cvt_pk_bf16_f32 v0, v0, v96
	ds_write_b16 v189, v0 offset:2624
	v_add_f32_e32 v0, v170, v38
	v_cvt_pk_bf16_f32 v0, v0, v96
	ds_write_b16 v189, v0 offset:2688
	v_add_f32_e32 v0, v170, v54
	v_cvt_pk_bf16_f32 v0, v0, v96
	ds_write_b16 v189, v0 offset:2752
	v_add_f32_e32 v0, v171, v7
	v_cvt_pk_bf16_f32 v0, v0, v96
	ds_write_b16 v189, v0 offset:2816
	v_add_f32_e32 v0, v171, v23
	v_cvt_pk_bf16_f32 v0, v0, v96
	ds_write_b16 v189, v0 offset:2880
	v_add_f32_e32 v0, v171, v39
	v_cvt_pk_bf16_f32 v0, v0, v96
	ds_write_b16 v189, v0 offset:2944
	v_add_f32_e32 v0, v171, v55
	v_cvt_pk_bf16_f32 v0, v0, v96
	ds_write_b16 v189, v0 offset:3008
	v_add_f32_e32 v0, v172, v8
	v_cvt_pk_bf16_f32 v0, v0, v96
	ds_write_b16 v189, v0 offset:4096
	v_add_f32_e32 v0, v172, v24
	v_cvt_pk_bf16_f32 v0, v0, v96
	ds_write_b16 v189, v0 offset:4160
	v_add_f32_e32 v0, v172, v40
	v_cvt_pk_bf16_f32 v0, v0, v96
	ds_write_b16 v189, v0 offset:4224
	v_add_f32_e32 v0, v172, v56
	v_cvt_pk_bf16_f32 v0, v0, v96
	ds_write_b16 v189, v0 offset:4288
	v_add_f32_e32 v0, v173, v9
	v_cvt_pk_bf16_f32 v0, v0, v96
	ds_write_b16 v189, v0 offset:4352
	v_add_f32_e32 v0, v173, v25
	v_cvt_pk_bf16_f32 v0, v0, v96
	ds_write_b16 v189, v0 offset:4416
	v_add_f32_e32 v0, v173, v41
	v_cvt_pk_bf16_f32 v0, v0, v96
	ds_write_b16 v189, v0 offset:4480
	v_add_f32_e32 v0, v173, v57
	v_cvt_pk_bf16_f32 v0, v0, v96
	ds_write_b16 v189, v0 offset:4544
	v_add_f32_e32 v0, v174, v10
	v_cvt_pk_bf16_f32 v0, v0, v96
	ds_write_b16 v189, v0 offset:4608
	v_add_f32_e32 v0, v174, v26
	v_cvt_pk_bf16_f32 v0, v0, v96
	ds_write_b16 v189, v0 offset:4672
	v_add_f32_e32 v0, v174, v42
	v_cvt_pk_bf16_f32 v0, v0, v96
	ds_write_b16 v189, v0 offset:4736
	v_add_f32_e32 v0, v174, v58
	v_cvt_pk_bf16_f32 v0, v0, v96
	ds_write_b16 v189, v0 offset:4800
	v_add_f32_e32 v0, v175, v11
	v_cvt_pk_bf16_f32 v0, v0, v96
	ds_write_b16 v189, v0 offset:4864
	v_add_f32_e32 v0, v175, v27
	v_cvt_pk_bf16_f32 v0, v0, v96
	ds_write_b16 v189, v0 offset:4928
	v_add_f32_e32 v0, v175, v43
	v_cvt_pk_bf16_f32 v0, v0, v96
	ds_write_b16 v189, v0 offset:4992
	v_add_f32_e32 v0, v175, v59
	v_cvt_pk_bf16_f32 v0, v0, v96
	ds_write_b16 v189, v0 offset:5056
	v_add_f32_e32 v0, v176, v12
	v_cvt_pk_bf16_f32 v0, v0, v96
	ds_write_b16 v189, v0 offset:6144
	v_add_f32_e32 v0, v176, v28
	v_cvt_pk_bf16_f32 v0, v0, v96
	ds_write_b16 v189, v0 offset:6208
	v_add_f32_e32 v0, v176, v44
	v_cvt_pk_bf16_f32 v0, v0, v96
	ds_write_b16 v189, v0 offset:6272
	v_add_f32_e32 v0, v176, v60
	v_cvt_pk_bf16_f32 v0, v0, v96
	ds_write_b16 v189, v0 offset:6336
	v_add_f32_e32 v0, v177, v13
	v_cvt_pk_bf16_f32 v0, v0, v96
	ds_write_b16 v189, v0 offset:6400
	v_add_f32_e32 v0, v177, v29
	v_cvt_pk_bf16_f32 v0, v0, v96
	ds_write_b16 v189, v0 offset:6464
	v_add_f32_e32 v0, v177, v45
	v_cvt_pk_bf16_f32 v0, v0, v96
	ds_write_b16 v189, v0 offset:6528
	v_add_f32_e32 v0, v177, v61
	v_cvt_pk_bf16_f32 v0, v0, v96
	ds_write_b16 v189, v0 offset:6592
	v_add_f32_e32 v0, v178, v14
	v_cvt_pk_bf16_f32 v0, v0, v96
	ds_write_b16 v189, v0 offset:6656
	v_add_f32_e32 v0, v178, v30
	v_cvt_pk_bf16_f32 v0, v0, v96
	ds_write_b16 v189, v0 offset:6720
	v_add_f32_e32 v0, v178, v46
	v_cvt_pk_bf16_f32 v0, v0, v96
	ds_write_b16 v189, v0 offset:6784
	v_add_f32_e32 v0, v178, v62
	v_cvt_pk_bf16_f32 v0, v0, v96
	ds_write_b16 v189, v0 offset:6848
	v_add_f32_e32 v0, v179, v15
	v_cvt_pk_bf16_f32 v0, v0, v96
	ds_write_b16 v189, v0 offset:6912
	v_add_f32_e32 v0, v179, v31
	v_cvt_pk_bf16_f32 v0, v0, v96
	ds_write_b16 v189, v0 offset:6976
	v_add_f32_e32 v0, v179, v47
	v_cvt_pk_bf16_f32 v0, v0, v96
	ds_write_b16 v189, v0 offset:7040
	v_add_f32_e32 v0, v179, v63
	v_cvt_pk_bf16_f32 v0, v0, v96
	ds_write_b16 v189, v0 offset:7104
	s_waitcnt lgkmcnt(0)
; __device__ __forceinline__ float bf2f(short s) { return __uint_as_float(((unsigned)(unsigned short)s) << 16); }
; __device__ __forceinline__ bf16x8 tobf8(f32x8 x) { u32x4 w = {cvtpk(x[0], x[1]), cvtpk(x[2], x[3]), cvtpk(x[4], x[5]), cvtpk(x[6], x[7])}; return *reinterpret_cast<bf16x8*>(&w); }
; __device__ __forceinline__ void spatial_phase(const Params& p, char* lds) {
;     ...
;                     const f32x4 g0 = *(const f32x4*)(p.ln_g + g * GD + cc), g1 = *(const f32x4*)(p.ln_g + g * GD + cc + 4), b0 = *(const f32x4*)(p.ln_b + g * GD + cc), b1 = *(const f32x4*)(p.ln_b + g * GD + cc + 4);
;     ...
;             for (int it = 0; it < 8; ++it) if (it < nit) { const int tl = it * 4 + er; const size_t row = rbase + 32 * tb + tl; const int col = g * GD + ch * 128 + ec;
;                 const bf16x8 mx = *(const bf16x8*)(stg + tl * 256 + ec * 2); f32x8 y;
; #pragma unroll
;                 for (int i = 0; i < 8; ++i) y[i] = bf2f(uu[it][i]) * bf2f(mx[i]);
;                 *(bf16x8*)(ACT + row * CW + col) = tobf8(y); }
	s_and_b32 s98, s79, 15
	s_lshl_b32 s98, s98, 10
	s_mov_b32 s99, 0
	v_lshl_add_u64 v[22:23], v[220:221], 0, s[98:99]
	v_lshl_add_u64 v[24:25], v[222:223], 0, s[98:99]
	global_load_dwordx4 v[32:35], v[22:23], off
	global_load_dwordx4 v[36:39], v[22:23], off offset:16
	global_load_dwordx4 v[48:51], v[22:23], off offset:512
	global_load_dwordx4 v[52:55], v[22:23], off offset:528
	global_load_dwordx4 v[40:43], v[24:25], off
	global_load_dwordx4 v[44:47], v[24:25], off offset:16
	global_load_dwordx4 v[56:59], v[24:25], off offset:512
	global_load_dwordx4 v[60:63], v[24:25], off offset:528
	s_mov_b32 s101, 1
	ds_read_b128 v[2:5], v226
	v_lshlrev_b32_e32 v7, 16, v120
	v_lshlrev_b32_e32 v8, 16, v121
	v_lshlrev_b32_e32 v9, 16, v122
	v_lshlrev_b32_e32 v10, 16, v123
	s_waitcnt lgkmcnt(0)
	v_lshlrev_b32_e32 v6, 16, v2
	v_mul_f32_e32 v6, v6, v7
	v_and_b32_e32 v7, 0xffff0000, v120
	v_and_b32_e32 v2, 0xffff0000, v2
	v_mul_f32_e32 v2, v2, v7
	v_lshlrev_b32_e32 v7, 16, v3
	v_mul_f32_e32 v7, v7, v8
	v_and_b32_e32 v8, 0xffff0000, v121
	v_and_b32_e32 v3, 0xffff0000, v3
	v_mul_f32_e32 v3, v3, v8
	v_lshlrev_b32_e32 v8, 16, v4
	v_mul_f32_e32 v8, v8, v9
	v_and_b32_e32 v9, 0xffff0000, v122
	v_and_b32_e32 v4, 0xffff0000, v4
	v_mul_f32_e32 v4, v4, v9
	v_lshlrev_b32_e32 v9, 16, v5
	v_mul_f32_e32 v9, v9, v10
	v_and_b32_e32 v10, 0xffff0000, v123
	v_and_b32_e32 v5, 0xffff0000, v5
	v_mul_f32_e32 v5, v5, v10
	s_add_u32 s40, s66, s48
	v_cvt_pk_bf16_f32 v2, v6, v2
	v_cvt_pk_bf16_f32 v3, v7, v3
	v_cvt_pk_bf16_f32 v4, v8, v4
	v_cvt_pk_bf16_f32 v5, v9, v5
	ds_read_b128 v[6:9], v227
	s_addc_u32 s41, s67, 0
	v_add_lshl_u32 v0, v195, s80, 1
	v_mov_b32_e32 v1, v96
	v_mov_b32_e32 v11, s41
	v_or_b32_e32 v10, s40, v188
	v_lshl_add_u64 v[0:1], s[86:87], 0, v[0:1]
	v_lshlrev_b64 v[10:11], 13, v[10:11]
	v_lshl_add_u64 v[10:11], v[0:1], 0, v[10:11]
	global_store_dwordx4 v[10:11], v[2:5], off
	v_lshlrev_b32_e32 v10, 16, v119
	v_mov_b32_e32 v11, s41
	s_waitcnt lgkmcnt(0)
	v_lshlrev_b32_e32 v2, 16, v6
	v_lshlrev_b32_e32 v3, 16, v116
	v_mul_f32_e32 v2, v2, v3
	v_and_b32_e32 v3, 0xffff0000, v116
	v_and_b32_e32 v4, 0xffff0000, v6
	v_mul_f32_e32 v3, v4, v3
	v_lshlrev_b32_e32 v4, 16, v7
	v_lshlrev_b32_e32 v5, 16, v117
	v_mul_f32_e32 v4, v4, v5
	v_and_b32_e32 v5, 0xffff0000, v117
	v_and_b32_e32 v6, 0xffff0000, v7
	v_mul_f32_e32 v5, v6, v5
	v_lshlrev_b32_e32 v6, 16, v8
	v_lshlrev_b32_e32 v7, 16, v118
	v_mul_f32_e32 v6, v6, v7
	v_and_b32_e32 v7, 0xffff0000, v118
	v_and_b32_e32 v8, 0xffff0000, v8
	v_mul_f32_e32 v7, v8, v7
	v_lshlrev_b32_e32 v8, 16, v9
	v_mul_f32_e32 v8, v8, v10
	v_and_b32_e32 v10, 0xffff0000, v119
	v_and_b32_e32 v9, 0xffff0000, v9
	v_mul_f32_e32 v9, v9, v10
	v_cvt_pk_bf16_f32 v2, v2, v3
	v_cvt_pk_bf16_f32 v3, v4, v5
	v_cvt_pk_bf16_f32 v4, v6, v7
	v_cvt_pk_bf16_f32 v5, v8, v9
	ds_read_b128 v[6:9], v228
	v_or_b32_e32 v10, s40, v206
	v_lshlrev_b64 v[10:11], 13, v[10:11]
	v_lshl_add_u64 v[10:11], v[0:1], 0, v[10:11]
	global_store_dwordx4 v[10:11], v[2:5], off
	v_lshlrev_b32_e32 v10, 16, v131
	v_mov_b32_e32 v11, s41
	s_waitcnt lgkmcnt(0)
	v_lshlrev_b32_e32 v2, 16, v6
	v_lshlrev_b32_e32 v3, 16, v128
	v_mul_f32_e32 v2, v2, v3
	v_and_b32_e32 v3, 0xffff0000, v128
	v_and_b32_e32 v4, 0xffff0000, v6
	v_mul_f32_e32 v3, v4, v3
	v_lshlrev_b32_e32 v4, 16, v7
	v_lshlrev_b32_e32 v5, 16, v129
	v_mul_f32_e32 v4, v4, v5
	v_and_b32_e32 v5, 0xffff0000, v129
	v_and_b32_e32 v6, 0xffff0000, v7
	v_mul_f32_e32 v5, v6, v5
	v_lshlrev_b32_e32 v6, 16, v8
	v_lshlrev_b32_e32 v7, 16, v130
	v_mul_f32_e32 v6, v6, v7
	v_and_b32_e32 v7, 0xffff0000, v130
	v_and_b32_e32 v8, 0xffff0000, v8
	v_mul_f32_e32 v7, v8, v7
	v_lshlrev_b32_e32 v8, 16, v9
	v_mul_f32_e32 v8, v8, v10
	v_and_b32_e32 v10, 0xffff0000, v131
	v_and_b32_e32 v9, 0xffff0000, v9
	v_mul_f32_e32 v9, v9, v10
	v_cvt_pk_bf16_f32 v2, v2, v3
	v_cvt_pk_bf16_f32 v3, v4, v5
	v_cvt_pk_bf16_f32 v4, v6, v7
	v_cvt_pk_bf16_f32 v5, v8, v9
	ds_read_b128 v[6:9], v229
	v_or_b32_e32 v10, s40, v208
	v_lshlrev_b64 v[10:11], 13, v[10:11]
	v_lshl_add_u64 v[10:11], v[0:1], 0, v[10:11]
	global_store_dwordx4 v[10:11], v[2:5], off
	s_and_b64 vcc, exec, s[38:39]
	s_waitcnt lgkmcnt(0)
	v_lshlrev_b32_e32 v2, 16, v6
	v_lshlrev_b32_e32 v3, 16, v124
	v_mul_f32_e32 v2, v2, v3
	v_and_b32_e32 v3, 0xffff0000, v124
	v_and_b32_e32 v4, 0xffff0000, v6
	v_mul_f32_e32 v3, v4, v3
	v_lshlrev_b32_e32 v4, 16, v7
	v_lshlrev_b32_e32 v5, 16, v125
	v_mul_f32_e32 v4, v4, v5
	v_and_b32_e32 v5, 0xffff0000, v125
	v_and_b32_e32 v6, 0xffff0000, v7
	v_mul_f32_e32 v5, v6, v5
	v_lshlrev_b32_e32 v6, 16, v8
	v_lshlrev_b32_e32 v7, 16, v126
	v_mul_f32_e32 v10, v6, v7
	v_and_b32_e32 v6, 0xffff0000, v126
	v_and_b32_e32 v7, 0xffff0000, v8
	v_mul_f32_e32 v8, v7, v6
	v_lshlrev_b32_e32 v6, 16, v9
	v_lshlrev_b32_e32 v7, 16, v127
	v_mul_f32_e32 v11, v6, v7
	v_and_b32_e32 v6, 0xffff0000, v127
	v_and_b32_e32 v7, 0xffff0000, v9
	v_mul_f32_e32 v9, v7, v6
	v_mov_b32_e32 v7, s41
	v_or_b32_e32 v6, s40, v210
	v_lshlrev_b64 v[6:7], 13, v[6:7]
	v_lshl_add_u64 v[6:7], v[0:1], 0, v[6:7]
	v_cvt_pk_bf16_f32 v2, v2, v3
	v_cvt_pk_bf16_f32 v3, v4, v5
	v_cvt_pk_bf16_f32 v4, v10, v8
	v_cvt_pk_bf16_f32 v5, v11, v9
	global_store_dwordx4 v[6:7], v[2:5], off
	s_waitcnt vmcnt(4)
	s_cbranch_vccnz .LBB0_1199
; __device__ __forceinline__ float bf2f(short s) { return __uint_as_float(((unsigned)(unsigned short)s) << 16); }
; __device__ __forceinline__ bf16x8 tobf8(f32x8 x) { u32x4 w = {cvtpk(x[0], x[1]), cvtpk(x[2], x[3]), cvtpk(x[4], x[5]), cvtpk(x[6], x[7])}; return *reinterpret_cast<bf16x8*>(&w); }
; __device__ __forceinline__ void spatial_phase(const Params& p, char* lds) {
;     ...
;             for (int it = 0; it < 8; ++it) if (it < nit) { const int tl = it * 4 + er; const size_t row = rbase + 32 * tb + tl; const int col = g * GD + ch * 128 + ec;
;                 const bf16x8 mx = *(const bf16x8*)(stg + tl * 256 + ec * 2); f32x8 y;
; #pragma unroll
;                 for (int i = 0; i < 8; ++i) y[i] = bf2f(uu[it][i]) * bf2f(mx[i]);
;                 *(bf16x8*)(ACT + row * CW + col) = tobf8(y); }
	ds_read_b128 v[2:5], v230
	v_lshlrev_b32_e32 v7, 16, v112
	s_waitcnt lgkmcnt(0)
	v_lshlrev_b32_e32 v6, 16, v2
	v_mul_f32_e32 v8, v6, v7
	v_and_b32_e32 v6, 0xffff0000, v112
	v_and_b32_e32 v2, 0xffff0000, v2
	v_mul_f32_e32 v2, v2, v6
	v_lshlrev_b32_e32 v6, 16, v3
	v_lshlrev_b32_e32 v7, 16, v113
	v_mul_f32_e32 v9, v6, v7
	v_and_b32_e32 v6, 0xffff0000, v113
	v_and_b32_e32 v3, 0xffff0000, v3
	v_mul_f32_e32 v3, v3, v6
	v_lshlrev_b32_e32 v6, 16, v4
	v_lshlrev_b32_e32 v7, 16, v114
	v_mul_f32_e32 v10, v6, v7
	v_and_b32_e32 v6, 0xffff0000, v114
	v_and_b32_e32 v4, 0xffff0000, v4
	v_mul_f32_e32 v4, v4, v6
	v_lshlrev_b32_e32 v6, 16, v5
	v_lshlrev_b32_e32 v7, 16, v115
	v_mul_f32_e32 v11, v6, v7
	v_and_b32_e32 v6, 0xffff0000, v115
	v_and_b32_e32 v5, 0xffff0000, v5
	v_mul_f32_e32 v5, v5, v6
	v_lshl_add_u64 v[6:7], s[40:41], 0, v[212:213]
	v_lshlrev_b64 v[6:7], 13, v[6:7]
	v_cvt_pk_bf16_f32 v2, v8, v2
	v_cvt_pk_bf16_f32 v3, v9, v3
	v_cvt_pk_bf16_f32 v4, v10, v4
	v_cvt_pk_bf16_f32 v5, v11, v5
	v_lshl_add_u64 v[6:7], v[0:1], 0, v[6:7]
	global_store_dwordx4 v[6:7], v[2:5], off
	ds_read_b128 v[2:5], v231
	v_lshlrev_b32_e32 v7, 16, v108
	s_waitcnt lgkmcnt(0)
	v_lshlrev_b32_e32 v6, 16, v2
	v_mul_f32_e32 v8, v6, v7
	v_and_b32_e32 v6, 0xffff0000, v108
	v_and_b32_e32 v2, 0xffff0000, v2
	v_mul_f32_e32 v2, v2, v6
	v_lshlrev_b32_e32 v6, 16, v3
	v_lshlrev_b32_e32 v7, 16, v109
	v_mul_f32_e32 v9, v6, v7
	v_and_b32_e32 v6, 0xffff0000, v109
	v_and_b32_e32 v3, 0xffff0000, v3
	v_mul_f32_e32 v3, v3, v6
	v_lshlrev_b32_e32 v6, 16, v4
	v_lshlrev_b32_e32 v7, 16, v110
	v_mul_f32_e32 v10, v6, v7
	v_and_b32_e32 v6, 0xffff0000, v110
	v_and_b32_e32 v4, 0xffff0000, v4
	v_mul_f32_e32 v4, v4, v6
	v_lshlrev_b32_e32 v6, 16, v5
	v_lshlrev_b32_e32 v7, 16, v111
	v_mul_f32_e32 v11, v6, v7
	v_and_b32_e32 v6, 0xffff0000, v111
	v_and_b32_e32 v5, 0xffff0000, v5
	v_mul_f32_e32 v5, v5, v6
	v_lshl_add_u64 v[6:7], s[40:41], 0, v[214:215]
	v_lshlrev_b64 v[6:7], 13, v[6:7]
	v_cvt_pk_bf16_f32 v2, v8, v2
	v_cvt_pk_bf16_f32 v3, v9, v3
	v_cvt_pk_bf16_f32 v4, v10, v4
	v_cvt_pk_bf16_f32 v5, v11, v5
	v_lshl_add_u64 v[6:7], v[0:1], 0, v[6:7]
	global_store_dwordx4 v[6:7], v[2:5], off
	ds_read_b128 v[2:5], v232
	v_lshlrev_b32_e32 v7, 16, v104
	s_waitcnt lgkmcnt(0)
	v_lshlrev_b32_e32 v6, 16, v2
	v_mul_f32_e32 v8, v6, v7
	v_and_b32_e32 v6, 0xffff0000, v104
	v_and_b32_e32 v2, 0xffff0000, v2
	v_mul_f32_e32 v2, v2, v6
	v_lshlrev_b32_e32 v6, 16, v3
	v_lshlrev_b32_e32 v7, 16, v105
	v_mul_f32_e32 v9, v6, v7
	v_and_b32_e32 v6, 0xffff0000, v105
	v_and_b32_e32 v3, 0xffff0000, v3
	v_mul_f32_e32 v3, v3, v6
	v_lshlrev_b32_e32 v6, 16, v4
	v_lshlrev_b32_e32 v7, 16, v106
	v_mul_f32_e32 v10, v6, v7
	v_and_b32_e32 v6, 0xffff0000, v106
	v_and_b32_e32 v4, 0xffff0000, v4
	v_mul_f32_e32 v4, v4, v6
	v_lshlrev_b32_e32 v6, 16, v5
	v_lshlrev_b32_e32 v7, 16, v107
	v_mul_f32_e32 v11, v6, v7
	v_and_b32_e32 v6, 0xffff0000, v107
	v_and_b32_e32 v5, 0xffff0000, v5
	v_mul_f32_e32 v5, v5, v6
	v_lshl_add_u64 v[6:7], s[40:41], 0, v[216:217]
	v_lshlrev_b64 v[6:7], 13, v[6:7]
	v_cvt_pk_bf16_f32 v2, v8, v2
	v_cvt_pk_bf16_f32 v3, v9, v3
	v_cvt_pk_bf16_f32 v4, v10, v4
	v_cvt_pk_bf16_f32 v5, v11, v5
	v_lshl_add_u64 v[6:7], v[0:1], 0, v[6:7]
	global_store_dwordx4 v[6:7], v[2:5], off
	ds_read_b128 v[2:5], v233
	v_lshlrev_b32_e32 v7, 16, v100
	s_waitcnt lgkmcnt(0)
	v_lshlrev_b32_e32 v6, 16, v2
	v_mul_f32_e32 v8, v6, v7
	v_and_b32_e32 v6, 0xffff0000, v100
	v_and_b32_e32 v2, 0xffff0000, v2
	v_mul_f32_e32 v2, v2, v6
	v_lshlrev_b32_e32 v6, 16, v3
	v_lshlrev_b32_e32 v7, 16, v101
	v_mul_f32_e32 v9, v6, v7
	v_and_b32_e32 v6, 0xffff0000, v101
	v_and_b32_e32 v3, 0xffff0000, v3
	v_mul_f32_e32 v3, v3, v6
	v_lshlrev_b32_e32 v6, 16, v4
	v_lshlrev_b32_e32 v7, 16, v102
	v_mul_f32_e32 v10, v6, v7
	v_and_b32_e32 v6, 0xffff0000, v102
	v_and_b32_e32 v4, 0xffff0000, v4
	v_mul_f32_e32 v4, v4, v6
	v_lshlrev_b32_e32 v6, 16, v5
	v_lshlrev_b32_e32 v7, 16, v103
	v_mul_f32_e32 v11, v6, v7
	v_and_b32_e32 v6, 0xffff0000, v103
	v_and_b32_e32 v5, 0xffff0000, v5
	v_mul_f32_e32 v5, v5, v6
	v_lshl_add_u64 v[6:7], s[40:41], 0, v[218:219]
	v_lshlrev_b64 v[6:7], 13, v[6:7]
	v_lshl_add_u64 v[0:1], v[0:1], 0, v[6:7]
	v_cvt_pk_bf16_f32 v2, v8, v2
	v_cvt_pk_bf16_f32 v3, v9, v3
	v_cvt_pk_bf16_f32 v4, v10, v4
	v_cvt_pk_bf16_f32 v5, v11, v5
	global_store_dwordx4 v[0:1], v[2:5], off
	s_branch .LBB0_1199
